# attention per-item prologue: first K/V tile global loads issued ahead of the buffer-reuse barrier
# speedup vs baseline: 1.0060x; 1.0013x over previous
.LBB0_111:
	v_mov_b32_e32 v209, 0xf0c9f2ca
	v_cmp_lt_f32_e32 vcc, v227, v209
	s_nop 1
	v_cndmask_b32_e64 v208, v227, 0, vcc
	v_sub_f32_e32 v234, 0, v208
	v_sub_f32_e32 v235, 0, v208
	v_sub_f32_e32 v236, 0, v208
	v_sub_f32_e32 v237, 0, v208
	v_sub_f32_e32 v238, 0, v208
	v_sub_f32_e32 v239, 0, v208
	v_sub_f32_e32 v240, 0, v208
	v_sub_f32_e32 v241, 0, v208
	v_sub_f32_e32 v242, 0, v208
	v_sub_f32_e32 v243, 0, v208
	v_sub_f32_e32 v244, 0, v208
	v_sub_f32_e32 v245, 0, v208
	v_sub_f32_e32 v246, 0, v208
	v_sub_f32_e32 v247, 0, v208
	v_sub_f32_e32 v248, 0, v208
	v_sub_f32_e32 v249, 0, v208
	v_mov_b32_e32 v0, 0x80
	v_sub_u32_e64 v0, s28, v0 clamp
	s_lshr_b32 s3, s24, 2
	v_readfirstlane_b32 s8, v0
	s_lshr_b32 s18, s8, 6
	s_min_u32 s8, s28, 0xd80
	s_addk_i32 s8, 0x280
	s_lshr_b32 s10, s8, 6
	s_and_b64 s[8:9], s[16:17], exec
	s_cselect_b32 s10, s10, 64
	s_and_b64 s[8:9], s[38:39], exec
	s_cselect_b32 s8, s10, 0
	s_and_b64 s[40:41], s[16:17], s[38:39]
	s_and_b64 s[10:11], s[40:41], exec
	s_cselect_b32 s10, s18, 0
	s_lshl_b32 s2, s2, 2
	s_add_i32 s9, s2, s3
	s_sub_i32 s11, s8, s10
	s_mul_i32 s2, s9, 0x88000
	s_mul_hi_i32 s3, s9, 0x88000
	s_add_u32 s2, s31, s2
	s_addc_u32 s3, s46, s3
	s_sub_i32 s18, 64, s11
	s_cmp_gt_i32 s11, 0
	s_cselect_b32 s94, s10, s18
	s_lshl_b64 s[18:19], s[94:95], 13
	s_add_u32 s18, s2, s18
	s_addc_u32 s19, s3, s19
	v_lshl_add_u64 v[6:7], s[18:19], 0, v[190:191]
	v_lshlrev_b32_e32 v0, 1, v184
	v_mov_b32_e32 v3, 0x88000
	v_lshl_add_u64 v[8:9], v[6:7], 0, v[0:1]
	v_mad_i64_i32 v[6:7], s[18:19], s9, v3, v[192:193]
	s_lshl_b32 s94, s94, 7
	v_lshl_add_u64 v[10:11], v[6:7], 0, s[94:95]
	v_lshl_add_u64 v[10:11], v[10:11], 0, v[0:1]
	global_load_dwordx4 v[176:179], v[8:9], off
	global_load_dwordx4 v[180:183], v[10:11], off
	s_barrier
	s_cmp_lt_i32 s11, -2
	s_waitcnt vmcnt(1)
	ds_write_b128 v219, v[176:179]
	s_waitcnt vmcnt(0)
	ds_write_b128 v219, v[180:183] offset:9216
	s_cbranch_scc1 .LBB0_113
	s_or_b32 s9, s10, 1
	s_sub_i32 s18, 0x41, s11
	s_cmp_gt_i32 s11, 1
	s_cselect_b32 s94, s9, s18
	s_lshl_b64 s[18:19], s[94:95], 13
	s_add_u32 s18, s2, s18
	s_addc_u32 s19, s3, s19
	v_lshl_add_u64 v[8:9], s[18:19], 0, v[190:191]
	s_lshl_b32 s94, s94, 7
	v_lshl_add_u64 v[8:9], v[8:9], 0, v[0:1]
	v_lshl_add_u64 v[10:11], v[6:7], 0, s[94:95]
	v_lshl_add_u64 v[10:11], v[10:11], 0, v[0:1]
	global_load_dwordx4 v[176:179], v[8:9], off
	global_load_dwordx4 v[180:183], v[10:11], off
